# P1 static order: third-round tiles rotated by 16 within each XCD class so no workgroup gets three gelu-epilogue tiles (max 2)
# baseline (speedup 1.0000x reference)
;     __device__ bool next(int i, Unit& u) const {
;         long L = (long)i * G + c;
;         if (L < nwg) {
;             int wgid = (int)L; { const int q = nwg / NXCD, r = nwg % NXCD, xcd = wgid % NXCD, off = wgid / NXCD; wgid = (xcd < r ? xcd * (q + 1) : r * (q + 1) + (xcd - r) * q) + off; }
;             const int nig = WGM * nN, gid = wgid / nig, fm = gid * WGM, gsz = (nM - fm) < WGM ? (nM - fm) : WGM;
;             u.pm = fm + ((wgid % nig) % gsz); u.pn = (wgid % nig) / gsz; u.kt0 = 0; u.nkt = nt; u.part = 0; return true;
; template <class Epi>
; __device__ __forceinline__ void gemm_phase(LAS unsigned char* lds, const Gemm g, const StaticOrder& S, const Epi& E) {
;     ...
;         const bool has_next = S.next(ui + 1, nxt);
.LBB0_112:
	s_add_i32 s72, s72, 1
	s_mul_i32 s6, s72, s75
	s_mul_hi_u32 s7, s72, s76
	s_add_i32 s7, s7, s6
	s_mul_i32 s6, s72, s76
	s_add_u32 s56, s6, s2
	s_addc_u32 s57, s7, s77
	v_cmp_gt_i64_e64 s[6:7], s[56:57], v[144:145]
	s_and_b64 vcc, exec, s[6:7]
	s_cbranch_vccnz .LBB0_118
	s_cmp_lg_u32 s72, 2
	s_cbranch_scc1 .Lp1_noperm
	s_and_b32 s9, s2, 7
	s_lshr_b32 s30, s2, 3
	s_add_i32 s30, s30, 16
	s_cmp_gt_u32 s9, 5
	s_cselect_b32 s33, 26, 27
	s_cmp_ge_u32 s30, s33
	s_cselect_b32 s31, s33, 0
	s_sub_i32 s30, s30, s31
	s_lshl_b32 s30, s30, 3
	s_add_i32 s30, s30, s9
	s_add_i32 s56, s30, 0x200
.Lp1_noperm:
	s_ashr_i32 s9, s56, 31
	s_lshr_b32 s9, s9, 29
	s_add_i32 s9, s56, s9
	s_and_b32 s30, s9, -8
	s_sub_i32 s33, s56, s30
	s_cmp_gt_i32 s33, 5
	s_mov_b64 s[30:31], -1
	s_cbranch_scc0 .LBB0_115
	s_mul_i32 s30, s33, 0x5a
	s_add_i32 s54, s30, 6
	s_mov_b64 s[30:31], 0
